# P0-row-pass-handwritten-all-row-loads-upfront
# baseline (speedup 1.0000x reference)
.LBB0_16:
	s_or_b64 exec, exec, s[10:11]
	v_readlane_b32 s16, v242, 31
	s_cmpk_gt_i32 s56, 0x21ff
	v_readlane_b32 s17, v242, 32
	v_readlane_b32 s18, v242, 33
	v_readlane_b32 s19, v242, 34
	v_readlane_b32 s26, v242, 41
	v_readlane_b32 s27, v242, 42
	v_readlane_b32 s20, v242, 35
	v_readlane_b32 s21, v242, 36
	v_readlane_b32 s22, v242, 37
	v_readlane_b32 s23, v242, 38
	v_readlane_b32 s24, v242, 39
	v_readlane_b32 s25, v242, 40
	v_readlane_b32 s28, v242, 43
	v_readlane_b32 s29, v242, 44
	v_readlane_b32 s30, v242, 45
	v_readlane_b32 s31, v242, 46
	s_cbranch_scc1 .LBB0_22
	v_lshlrev_b32_e32 v216, 4, v142
	v_add_u32_e32 v217, 0x1000, v216
	v_mov_b32_e32 v218, 0x358637bd
	v_xor_b32_e32 v130, 1, v142
	v_lshlrev_b32_e32 v208, 2, v130
	v_xor_b32_e32 v130, 2, v142
	v_lshlrev_b32_e32 v209, 2, v130
	v_xor_b32_e32 v130, 4, v142
	v_lshlrev_b32_e32 v210, 2, v130
	v_xor_b32_e32 v130, 8, v142
	v_lshlrev_b32_e32 v211, 2, v130
	v_xor_b32_e32 v130, 16, v142
	v_lshlrev_b32_e32 v212, 2, v130
	v_xor_b32_e32 v130, 32, v142
	v_lshlrev_b32_e32 v213, 2, v130
	global_load_dwordx4 v[2:5], v216, s[26:27] offset:0
	global_load_dwordx4 v[6:9], v216, s[26:27] offset:1024
	global_load_dwordx4 v[10:13], v216, s[26:27] offset:2048
	global_load_dwordx4 v[14:17], v216, s[26:27] offset:3072
	global_load_dwordx4 v[18:21], v217, s[26:27] offset:0
	global_load_dwordx4 v[22:25], v217, s[26:27] offset:1024
	global_load_dwordx4 v[26:29], v217, s[26:27] offset:2048
	global_load_dwordx4 v[30:33], v217, s[26:27] offset:3072
	s_ashr_i32 s57, s56, 31
	s_lshl_b64 s[0:1], s[56:57], 13
	s_add_u32 s8, s16, s0
	s_addc_u32 s9, s17, s1
	global_load_dwordx4 v[34:37], v216, s[8:9] offset:0
	global_load_dwordx4 v[38:41], v216, s[8:9] offset:1024
	global_load_dwordx4 v[42:45], v216, s[8:9] offset:2048
	global_load_dwordx4 v[46:49], v216, s[8:9] offset:3072
	global_load_dwordx4 v[50:53], v217, s[8:9] offset:0
	global_load_dwordx4 v[54:57], v217, s[8:9] offset:1024
	global_load_dwordx4 v[58:61], v217, s[8:9] offset:2048
	global_load_dwordx4 v[62:65], v217, s[8:9] offset:3072
	s_add_u32 s8, s8, 0x1000000
	s_addc_u32 s9, s9, 0
	global_load_dwordx4 v[66:69], v216, s[8:9] offset:0
	global_load_dwordx4 v[70:73], v216, s[8:9] offset:1024
	global_load_dwordx4 v[74:77], v216, s[8:9] offset:2048
	global_load_dwordx4 v[78:81], v216, s[8:9] offset:3072
	global_load_dwordx4 v[82:85], v217, s[8:9] offset:0
	global_load_dwordx4 v[86:89], v217, s[8:9] offset:1024
	global_load_dwordx4 v[90:93], v217, s[8:9] offset:2048
	global_load_dwordx4 v[94:97], v217, s[8:9] offset:3072
	s_add_u32 s8, s8, 0x1000000
	s_addc_u32 s9, s9, 0
	global_load_dwordx4 v[98:101], v216, s[8:9] offset:0
	global_load_dwordx4 v[102:105], v216, s[8:9] offset:1024
	global_load_dwordx4 v[106:109], v216, s[8:9] offset:2048
	global_load_dwordx4 v[110:113], v216, s[8:9] offset:3072
	global_load_dwordx4 v[114:117], v217, s[8:9] offset:0
	global_load_dwordx4 v[118:121], v217, s[8:9] offset:1024
	global_load_dwordx4 v[122:125], v217, s[8:9] offset:2048
	global_load_dwordx4 v[126:129], v217, s[8:9] offset:3072
	s_add_u32 s8, s8, 0x1000000
	s_addc_u32 s9, s9, 0
	global_load_dwordx4 v[144:147], v216, s[8:9] offset:0
	global_load_dwordx4 v[148:151], v216, s[8:9] offset:1024
	global_load_dwordx4 v[152:155], v216, s[8:9] offset:2048
	global_load_dwordx4 v[156:159], v216, s[8:9] offset:3072
	global_load_dwordx4 v[160:163], v217, s[8:9] offset:0
	global_load_dwordx4 v[164:167], v217, s[8:9] offset:1024
	global_load_dwordx4 v[168:171], v217, s[8:9] offset:2048
	global_load_dwordx4 v[172:175], v217, s[8:9] offset:3072
	s_cmpk_gt_i32 s56, 0x1ff
	s_cbranch_scc1 .Lp0r_no5
	s_add_u32 s8, s18, s0
	s_addc_u32 s9, s19, s1
	global_load_dwordx4 v[176:179], v216, s[8:9] offset:0
	global_load_dwordx4 v[180:183], v216, s[8:9] offset:1024
	global_load_dwordx4 v[184:187], v216, s[8:9] offset:2048
	global_load_dwordx4 v[188:191], v216, s[8:9] offset:3072
	global_load_dwordx4 v[192:195], v217, s[8:9] offset:0
	global_load_dwordx4 v[196:199], v217, s[8:9] offset:1024
	global_load_dwordx4 v[200:203], v217, s[8:9] offset:2048
	global_load_dwordx4 v[204:207], v217, s[8:9] offset:3072
.Lp0r_no5:
	s_lshl_b64 s[0:1], s[56:57], 12
	s_add_u32 s0, s70, s0
	s_addc_u32 s1, s71, s1
	s_add_u32 s0, s0, 0xc000000
	s_addc_u32 s1, s1, 0
	v_lshlrev_b32_e32 v214, 3, v142
	v_mov_b32_e32 v215, 0
	v_lshl_add_u64 v[214:215], s[0:1], 0, v[214:215]
	s_mov_b64 s[0:1], 0x800000
	s_mov_b32 s3, 0x800000
	s_waitcnt vmcnt(24)
	v_mul_f32_e32 v130, v34, v34
	v_fmac_f32_e32 v130, v35, v35
	v_mul_f32_e32 v131, v36, v36
	v_fmac_f32_e32 v131, v37, v37
	v_add_f32_e32 v130, v130, v131
	v_mul_f32_e32 v131, v38, v38
	v_fmac_f32_e32 v131, v39, v39
	v_mul_f32_e32 v134, v40, v40
	v_fmac_f32_e32 v134, v41, v41
	v_add_f32_e32 v131, v131, v134
	v_add_f32_e32 v130, v130, v131
	v_mul_f32_e32 v131, v42, v42
	v_fmac_f32_e32 v131, v43, v43
	v_mul_f32_e32 v134, v44, v44
	v_fmac_f32_e32 v134, v45, v45
	v_add_f32_e32 v131, v131, v134
	v_add_f32_e32 v130, v130, v131
	v_mul_f32_e32 v131, v46, v46
	v_fmac_f32_e32 v131, v47, v47
	v_mul_f32_e32 v134, v48, v48
	v_fmac_f32_e32 v134, v49, v49
	v_add_f32_e32 v131, v131, v134
	v_add_f32_e32 v130, v130, v131
	v_mul_f32_e32 v131, v50, v50
	v_fmac_f32_e32 v131, v51, v51
	v_mul_f32_e32 v134, v52, v52
	v_fmac_f32_e32 v134, v53, v53
	v_add_f32_e32 v131, v131, v134
	v_add_f32_e32 v130, v130, v131
	v_mul_f32_e32 v131, v54, v54
	v_fmac_f32_e32 v131, v55, v55
	v_mul_f32_e32 v134, v56, v56
	v_fmac_f32_e32 v134, v57, v57
	v_add_f32_e32 v131, v131, v134
	v_add_f32_e32 v130, v130, v131
	v_mul_f32_e32 v131, v58, v58
	v_fmac_f32_e32 v131, v59, v59
	v_mul_f32_e32 v134, v60, v60
	v_fmac_f32_e32 v134, v61, v61
	v_add_f32_e32 v131, v131, v134
	v_add_f32_e32 v130, v130, v131
	v_mul_f32_e32 v131, v62, v62
	v_fmac_f32_e32 v131, v63, v63
	v_mul_f32_e32 v134, v64, v64
	v_fmac_f32_e32 v134, v65, v65
	v_add_f32_e32 v131, v131, v134
	v_add_f32_e32 v130, v130, v131
	ds_bpermute_b32 v131, v208, v130
	s_waitcnt lgkmcnt(0)
	v_add_f32_e32 v130, v130, v131
	ds_bpermute_b32 v131, v209, v130
	s_waitcnt lgkmcnt(0)
	v_add_f32_e32 v130, v130, v131
	ds_bpermute_b32 v131, v210, v130
	s_waitcnt lgkmcnt(0)
	v_add_f32_e32 v130, v130, v131
	ds_bpermute_b32 v131, v211, v130
	s_waitcnt lgkmcnt(0)
	v_add_f32_e32 v130, v130, v131
	ds_bpermute_b32 v131, v212, v130
	s_waitcnt lgkmcnt(0)
	v_add_f32_e32 v130, v130, v131
	ds_bpermute_b32 v131, v213, v130
	s_waitcnt lgkmcnt(0)
	v_add_f32_e32 v130, v130, v131
	v_fmamk_f32 v130, v130, 0x3a000000, v218
	v_mul_f32_e32 v131, 0x4b800000, v130
	v_cmp_gt_f32_e32 vcc, s3, v130
	s_nop 1
	v_cndmask_b32_e32 v130, v130, v131, vcc
	v_rsq_f32_e32 v130, v130
	s_nop 0
	v_mul_f32_e32 v131, 0x45800000, v130
	v_cndmask_b32_e32 v132, v130, v131, vcc
	v_pk_mul_f32 v[34:35], v[34:35], v[132:133] op_sel_hi:[1,0]
	v_pk_mul_f32 v[34:35], v[2:3], v[34:35]
	v_pk_mul_f32 v[36:37], v[36:37], v[132:133] op_sel_hi:[1,0]
	v_pk_mul_f32 v[36:37], v[4:5], v[36:37]
	v_pk_mul_f32 v[38:39], v[38:39], v[132:133] op_sel_hi:[1,0]
	v_pk_mul_f32 v[38:39], v[6:7], v[38:39]
	v_pk_mul_f32 v[40:41], v[40:41], v[132:133] op_sel_hi:[1,0]
	v_pk_mul_f32 v[40:41], v[8:9], v[40:41]
	v_pk_mul_f32 v[42:43], v[42:43], v[132:133] op_sel_hi:[1,0]
	v_pk_mul_f32 v[42:43], v[10:11], v[42:43]
	v_pk_mul_f32 v[44:45], v[44:45], v[132:133] op_sel_hi:[1,0]
	v_pk_mul_f32 v[44:45], v[12:13], v[44:45]
	v_pk_mul_f32 v[46:47], v[46:47], v[132:133] op_sel_hi:[1,0]
	v_pk_mul_f32 v[46:47], v[14:15], v[46:47]
	v_pk_mul_f32 v[48:49], v[48:49], v[132:133] op_sel_hi:[1,0]
	v_pk_mul_f32 v[48:49], v[16:17], v[48:49]
	v_pk_mul_f32 v[50:51], v[50:51], v[132:133] op_sel_hi:[1,0]
	v_pk_mul_f32 v[50:51], v[18:19], v[50:51]
	v_pk_mul_f32 v[52:53], v[52:53], v[132:133] op_sel_hi:[1,0]
	v_pk_mul_f32 v[52:53], v[20:21], v[52:53]
	v_pk_mul_f32 v[54:55], v[54:55], v[132:133] op_sel_hi:[1,0]
	v_pk_mul_f32 v[54:55], v[22:23], v[54:55]
	v_pk_mul_f32 v[56:57], v[56:57], v[132:133] op_sel_hi:[1,0]
	v_pk_mul_f32 v[56:57], v[24:25], v[56:57]
	v_pk_mul_f32 v[58:59], v[58:59], v[132:133] op_sel_hi:[1,0]
	v_pk_mul_f32 v[58:59], v[26:27], v[58:59]
	v_pk_mul_f32 v[60:61], v[60:61], v[132:133] op_sel_hi:[1,0]
	v_pk_mul_f32 v[60:61], v[28:29], v[60:61]
	v_pk_mul_f32 v[62:63], v[62:63], v[132:133] op_sel_hi:[1,0]
	v_pk_mul_f32 v[62:63], v[30:31], v[62:63]
	v_pk_mul_f32 v[64:65], v[64:65], v[132:133] op_sel_hi:[1,0]
	v_pk_mul_f32 v[64:65], v[32:33], v[64:65]
	v_cvt_pk_bf16_f32 v34, v34, v35
	v_cvt_pk_bf16_f32 v35, v36, v37
	v_cvt_pk_bf16_f32 v38, v38, v39
	v_cvt_pk_bf16_f32 v39, v40, v41
	v_cvt_pk_bf16_f32 v42, v42, v43
	v_cvt_pk_bf16_f32 v43, v44, v45
	v_cvt_pk_bf16_f32 v46, v46, v47
	v_cvt_pk_bf16_f32 v47, v48, v49
	v_cvt_pk_bf16_f32 v50, v50, v51
	v_cvt_pk_bf16_f32 v51, v52, v53
	v_cvt_pk_bf16_f32 v54, v54, v55
	v_cvt_pk_bf16_f32 v55, v56, v57
	v_cvt_pk_bf16_f32 v58, v58, v59
	v_cvt_pk_bf16_f32 v59, v60, v61
	v_cvt_pk_bf16_f32 v62, v62, v63
	v_cvt_pk_bf16_f32 v63, v64, v65
	global_store_dwordx2 v[214:215], v[34:35], off offset:0
	global_store_dwordx2 v[214:215], v[38:39], off offset:512
	global_store_dwordx2 v[214:215], v[42:43], off offset:1024
	global_store_dwordx2 v[214:215], v[46:47], off offset:1536
	global_store_dwordx2 v[214:215], v[50:51], off offset:2048
	global_store_dwordx2 v[214:215], v[54:55], off offset:2560
	global_store_dwordx2 v[214:215], v[58:59], off offset:3072
	global_store_dwordx2 v[214:215], v[62:63], off offset:3584
	v_lshl_add_u64 v[214:215], v[214:215], 0, s[0:1]
	s_waitcnt vmcnt(24)
	v_mul_f32_e32 v130, v66, v66
	v_fmac_f32_e32 v130, v67, v67
	v_mul_f32_e32 v131, v68, v68
	v_fmac_f32_e32 v131, v69, v69
	v_add_f32_e32 v130, v130, v131
	v_mul_f32_e32 v131, v70, v70
	v_fmac_f32_e32 v131, v71, v71
	v_mul_f32_e32 v134, v72, v72
	v_fmac_f32_e32 v134, v73, v73
	v_add_f32_e32 v131, v131, v134
	v_add_f32_e32 v130, v130, v131
	v_mul_f32_e32 v131, v74, v74
	v_fmac_f32_e32 v131, v75, v75
	v_mul_f32_e32 v134, v76, v76
	v_fmac_f32_e32 v134, v77, v77
	v_add_f32_e32 v131, v131, v134
	v_add_f32_e32 v130, v130, v131
	v_mul_f32_e32 v131, v78, v78
	v_fmac_f32_e32 v131, v79, v79
	v_mul_f32_e32 v134, v80, v80
	v_fmac_f32_e32 v134, v81, v81
	v_add_f32_e32 v131, v131, v134
	v_add_f32_e32 v130, v130, v131
	v_mul_f32_e32 v131, v82, v82
	v_fmac_f32_e32 v131, v83, v83
	v_mul_f32_e32 v134, v84, v84
	v_fmac_f32_e32 v134, v85, v85
	v_add_f32_e32 v131, v131, v134
	v_add_f32_e32 v130, v130, v131
	v_mul_f32_e32 v131, v86, v86
	v_fmac_f32_e32 v131, v87, v87
	v_mul_f32_e32 v134, v88, v88
	v_fmac_f32_e32 v134, v89, v89
	v_add_f32_e32 v131, v131, v134
	v_add_f32_e32 v130, v130, v131
	v_mul_f32_e32 v131, v90, v90
	v_fmac_f32_e32 v131, v91, v91
	v_mul_f32_e32 v134, v92, v92
	v_fmac_f32_e32 v134, v93, v93
	v_add_f32_e32 v131, v131, v134
	v_add_f32_e32 v130, v130, v131
	v_mul_f32_e32 v131, v94, v94
	v_fmac_f32_e32 v131, v95, v95
	v_mul_f32_e32 v134, v96, v96
	v_fmac_f32_e32 v134, v97, v97
	v_add_f32_e32 v131, v131, v134
	v_add_f32_e32 v130, v130, v131
	ds_bpermute_b32 v131, v208, v130
	s_waitcnt lgkmcnt(0)
	v_add_f32_e32 v130, v130, v131
	ds_bpermute_b32 v131, v209, v130
	s_waitcnt lgkmcnt(0)
	v_add_f32_e32 v130, v130, v131
	ds_bpermute_b32 v131, v210, v130
	s_waitcnt lgkmcnt(0)
	v_add_f32_e32 v130, v130, v131
	ds_bpermute_b32 v131, v211, v130
	s_waitcnt lgkmcnt(0)
	v_add_f32_e32 v130, v130, v131
	ds_bpermute_b32 v131, v212, v130
	s_waitcnt lgkmcnt(0)
	v_add_f32_e32 v130, v130, v131
	ds_bpermute_b32 v131, v213, v130
	s_waitcnt lgkmcnt(0)
	v_add_f32_e32 v130, v130, v131
	v_fmamk_f32 v130, v130, 0x3a000000, v218
	v_mul_f32_e32 v131, 0x4b800000, v130
	v_cmp_gt_f32_e32 vcc, s3, v130
	s_nop 1
	v_cndmask_b32_e32 v130, v130, v131, vcc
	v_rsq_f32_e32 v130, v130
	s_nop 0
	v_mul_f32_e32 v131, 0x45800000, v130
	v_cndmask_b32_e32 v132, v130, v131, vcc
	v_pk_mul_f32 v[66:67], v[66:67], v[132:133] op_sel_hi:[1,0]
	v_pk_mul_f32 v[66:67], v[2:3], v[66:67]
	v_pk_mul_f32 v[68:69], v[68:69], v[132:133] op_sel_hi:[1,0]
	v_pk_mul_f32 v[68:69], v[4:5], v[68:69]
	v_pk_mul_f32 v[70:71], v[70:71], v[132:133] op_sel_hi:[1,0]
	v_pk_mul_f32 v[70:71], v[6:7], v[70:71]
	v_pk_mul_f32 v[72:73], v[72:73], v[132:133] op_sel_hi:[1,0]
	v_pk_mul_f32 v[72:73], v[8:9], v[72:73]
	v_pk_mul_f32 v[74:75], v[74:75], v[132:133] op_sel_hi:[1,0]
	v_pk_mul_f32 v[74:75], v[10:11], v[74:75]
	v_pk_mul_f32 v[76:77], v[76:77], v[132:133] op_sel_hi:[1,0]
	v_pk_mul_f32 v[76:77], v[12:13], v[76:77]
	v_pk_mul_f32 v[78:79], v[78:79], v[132:133] op_sel_hi:[1,0]
	v_pk_mul_f32 v[78:79], v[14:15], v[78:79]
	v_pk_mul_f32 v[80:81], v[80:81], v[132:133] op_sel_hi:[1,0]
	v_pk_mul_f32 v[80:81], v[16:17], v[80:81]
	v_pk_mul_f32 v[82:83], v[82:83], v[132:133] op_sel_hi:[1,0]
	v_pk_mul_f32 v[82:83], v[18:19], v[82:83]
	v_pk_mul_f32 v[84:85], v[84:85], v[132:133] op_sel_hi:[1,0]
	v_pk_mul_f32 v[84:85], v[20:21], v[84:85]
	v_pk_mul_f32 v[86:87], v[86:87], v[132:133] op_sel_hi:[1,0]
	v_pk_mul_f32 v[86:87], v[22:23], v[86:87]
	v_pk_mul_f32 v[88:89], v[88:89], v[132:133] op_sel_hi:[1,0]
	v_pk_mul_f32 v[88:89], v[24:25], v[88:89]
	v_pk_mul_f32 v[90:91], v[90:91], v[132:133] op_sel_hi:[1,0]
	v_pk_mul_f32 v[90:91], v[26:27], v[90:91]
	v_pk_mul_f32 v[92:93], v[92:93], v[132:133] op_sel_hi:[1,0]
	v_pk_mul_f32 v[92:93], v[28:29], v[92:93]
	v_pk_mul_f32 v[94:95], v[94:95], v[132:133] op_sel_hi:[1,0]
	v_pk_mul_f32 v[94:95], v[30:31], v[94:95]
	v_pk_mul_f32 v[96:97], v[96:97], v[132:133] op_sel_hi:[1,0]
	v_pk_mul_f32 v[96:97], v[32:33], v[96:97]
	v_cvt_pk_bf16_f32 v66, v66, v67
	v_cvt_pk_bf16_f32 v67, v68, v69
	v_cvt_pk_bf16_f32 v70, v70, v71
	v_cvt_pk_bf16_f32 v71, v72, v73
	v_cvt_pk_bf16_f32 v74, v74, v75
	v_cvt_pk_bf16_f32 v75, v76, v77
	v_cvt_pk_bf16_f32 v78, v78, v79
	v_cvt_pk_bf16_f32 v79, v80, v81
	v_cvt_pk_bf16_f32 v82, v82, v83
	v_cvt_pk_bf16_f32 v83, v84, v85
	v_cvt_pk_bf16_f32 v86, v86, v87
	v_cvt_pk_bf16_f32 v87, v88, v89
	v_cvt_pk_bf16_f32 v90, v90, v91
	v_cvt_pk_bf16_f32 v91, v92, v93
	v_cvt_pk_bf16_f32 v94, v94, v95
	v_cvt_pk_bf16_f32 v95, v96, v97
	global_store_dwordx2 v[214:215], v[66:67], off offset:0
	global_store_dwordx2 v[214:215], v[70:71], off offset:512
	global_store_dwordx2 v[214:215], v[74:75], off offset:1024
	global_store_dwordx2 v[214:215], v[78:79], off offset:1536
	global_store_dwordx2 v[214:215], v[82:83], off offset:2048
	global_store_dwordx2 v[214:215], v[86:87], off offset:2560
	global_store_dwordx2 v[214:215], v[90:91], off offset:3072
	global_store_dwordx2 v[214:215], v[94:95], off offset:3584
	v_lshl_add_u64 v[214:215], v[214:215], 0, s[0:1]
	s_waitcnt vmcnt(24)
	v_mul_f32_e32 v130, v98, v98
	v_fmac_f32_e32 v130, v99, v99
	v_mul_f32_e32 v131, v100, v100
	v_fmac_f32_e32 v131, v101, v101
	v_add_f32_e32 v130, v130, v131
	v_mul_f32_e32 v131, v102, v102
	v_fmac_f32_e32 v131, v103, v103
	v_mul_f32_e32 v134, v104, v104
	v_fmac_f32_e32 v134, v105, v105
	v_add_f32_e32 v131, v131, v134
	v_add_f32_e32 v130, v130, v131
	v_mul_f32_e32 v131, v106, v106
	v_fmac_f32_e32 v131, v107, v107
	v_mul_f32_e32 v134, v108, v108
	v_fmac_f32_e32 v134, v109, v109
	v_add_f32_e32 v131, v131, v134
	v_add_f32_e32 v130, v130, v131
	v_mul_f32_e32 v131, v110, v110
	v_fmac_f32_e32 v131, v111, v111
	v_mul_f32_e32 v134, v112, v112
	v_fmac_f32_e32 v134, v113, v113
	v_add_f32_e32 v131, v131, v134
	v_add_f32_e32 v130, v130, v131
	v_mul_f32_e32 v131, v114, v114
	v_fmac_f32_e32 v131, v115, v115
	v_mul_f32_e32 v134, v116, v116
	v_fmac_f32_e32 v134, v117, v117
	v_add_f32_e32 v131, v131, v134
	v_add_f32_e32 v130, v130, v131
	v_mul_f32_e32 v131, v118, v118
	v_fmac_f32_e32 v131, v119, v119
	v_mul_f32_e32 v134, v120, v120
	v_fmac_f32_e32 v134, v121, v121
	v_add_f32_e32 v131, v131, v134
	v_add_f32_e32 v130, v130, v131
	v_mul_f32_e32 v131, v122, v122
	v_fmac_f32_e32 v131, v123, v123
	v_mul_f32_e32 v134, v124, v124
	v_fmac_f32_e32 v134, v125, v125
	v_add_f32_e32 v131, v131, v134
	v_add_f32_e32 v130, v130, v131
	v_mul_f32_e32 v131, v126, v126
	v_fmac_f32_e32 v131, v127, v127
	v_mul_f32_e32 v134, v128, v128
	v_fmac_f32_e32 v134, v129, v129
	v_add_f32_e32 v131, v131, v134
	v_add_f32_e32 v130, v130, v131
	ds_bpermute_b32 v131, v208, v130
	s_waitcnt lgkmcnt(0)
	v_add_f32_e32 v130, v130, v131
	ds_bpermute_b32 v131, v209, v130
	s_waitcnt lgkmcnt(0)
	v_add_f32_e32 v130, v130, v131
	ds_bpermute_b32 v131, v210, v130
	s_waitcnt lgkmcnt(0)
	v_add_f32_e32 v130, v130, v131
	ds_bpermute_b32 v131, v211, v130
	s_waitcnt lgkmcnt(0)
	v_add_f32_e32 v130, v130, v131
	ds_bpermute_b32 v131, v212, v130
	s_waitcnt lgkmcnt(0)
	v_add_f32_e32 v130, v130, v131
	ds_bpermute_b32 v131, v213, v130
	s_waitcnt lgkmcnt(0)
	v_add_f32_e32 v130, v130, v131
	v_fmamk_f32 v130, v130, 0x3a000000, v218
	v_mul_f32_e32 v131, 0x4b800000, v130
	v_cmp_gt_f32_e32 vcc, s3, v130
	s_nop 1
	v_cndmask_b32_e32 v130, v130, v131, vcc
	v_rsq_f32_e32 v130, v130
	s_nop 0
	v_mul_f32_e32 v131, 0x45800000, v130
	v_cndmask_b32_e32 v132, v130, v131, vcc
	v_pk_mul_f32 v[98:99], v[98:99], v[132:133] op_sel_hi:[1,0]
	v_pk_mul_f32 v[98:99], v[2:3], v[98:99]
	v_pk_mul_f32 v[100:101], v[100:101], v[132:133] op_sel_hi:[1,0]
	v_pk_mul_f32 v[100:101], v[4:5], v[100:101]
	v_pk_mul_f32 v[102:103], v[102:103], v[132:133] op_sel_hi:[1,0]
	v_pk_mul_f32 v[102:103], v[6:7], v[102:103]
	v_pk_mul_f32 v[104:105], v[104:105], v[132:133] op_sel_hi:[1,0]
	v_pk_mul_f32 v[104:105], v[8:9], v[104:105]
	v_pk_mul_f32 v[106:107], v[106:107], v[132:133] op_sel_hi:[1,0]
	v_pk_mul_f32 v[106:107], v[10:11], v[106:107]
	v_pk_mul_f32 v[108:109], v[108:109], v[132:133] op_sel_hi:[1,0]
	v_pk_mul_f32 v[108:109], v[12:13], v[108:109]
	v_pk_mul_f32 v[110:111], v[110:111], v[132:133] op_sel_hi:[1,0]
	v_pk_mul_f32 v[110:111], v[14:15], v[110:111]
	v_pk_mul_f32 v[112:113], v[112:113], v[132:133] op_sel_hi:[1,0]
	v_pk_mul_f32 v[112:113], v[16:17], v[112:113]
	v_pk_mul_f32 v[114:115], v[114:115], v[132:133] op_sel_hi:[1,0]
	v_pk_mul_f32 v[114:115], v[18:19], v[114:115]
	v_pk_mul_f32 v[116:117], v[116:117], v[132:133] op_sel_hi:[1,0]
	v_pk_mul_f32 v[116:117], v[20:21], v[116:117]
	v_pk_mul_f32 v[118:119], v[118:119], v[132:133] op_sel_hi:[1,0]
	v_pk_mul_f32 v[118:119], v[22:23], v[118:119]
	v_pk_mul_f32 v[120:121], v[120:121], v[132:133] op_sel_hi:[1,0]
	v_pk_mul_f32 v[120:121], v[24:25], v[120:121]
	v_pk_mul_f32 v[122:123], v[122:123], v[132:133] op_sel_hi:[1,0]
	v_pk_mul_f32 v[122:123], v[26:27], v[122:123]
	v_pk_mul_f32 v[124:125], v[124:125], v[132:133] op_sel_hi:[1,0]
	v_pk_mul_f32 v[124:125], v[28:29], v[124:125]
	v_pk_mul_f32 v[126:127], v[126:127], v[132:133] op_sel_hi:[1,0]
	v_pk_mul_f32 v[126:127], v[30:31], v[126:127]
	v_pk_mul_f32 v[128:129], v[128:129], v[132:133] op_sel_hi:[1,0]
	v_pk_mul_f32 v[128:129], v[32:33], v[128:129]
	v_cvt_pk_bf16_f32 v98, v98, v99
	v_cvt_pk_bf16_f32 v99, v100, v101
	v_cvt_pk_bf16_f32 v102, v102, v103
	v_cvt_pk_bf16_f32 v103, v104, v105
	v_cvt_pk_bf16_f32 v106, v106, v107
	v_cvt_pk_bf16_f32 v107, v108, v109
	v_cvt_pk_bf16_f32 v110, v110, v111
	v_cvt_pk_bf16_f32 v111, v112, v113
	v_cvt_pk_bf16_f32 v114, v114, v115
	v_cvt_pk_bf16_f32 v115, v116, v117
	v_cvt_pk_bf16_f32 v118, v118, v119
	v_cvt_pk_bf16_f32 v119, v120, v121
	v_cvt_pk_bf16_f32 v122, v122, v123
	v_cvt_pk_bf16_f32 v123, v124, v125
	v_cvt_pk_bf16_f32 v126, v126, v127
	v_cvt_pk_bf16_f32 v127, v128, v129
	global_store_dwordx2 v[214:215], v[98:99], off offset:0
	global_store_dwordx2 v[214:215], v[102:103], off offset:512
	global_store_dwordx2 v[214:215], v[106:107], off offset:1024
	global_store_dwordx2 v[214:215], v[110:111], off offset:1536
	global_store_dwordx2 v[214:215], v[114:115], off offset:2048
	global_store_dwordx2 v[214:215], v[118:119], off offset:2560
	global_store_dwordx2 v[214:215], v[122:123], off offset:3072
	global_store_dwordx2 v[214:215], v[126:127], off offset:3584
	v_lshl_add_u64 v[214:215], v[214:215], 0, s[0:1]
	s_waitcnt vmcnt(24)
	v_mul_f32_e32 v130, v144, v144
	v_fmac_f32_e32 v130, v145, v145
	v_mul_f32_e32 v131, v146, v146
	v_fmac_f32_e32 v131, v147, v147
	v_add_f32_e32 v130, v130, v131
	v_mul_f32_e32 v131, v148, v148
	v_fmac_f32_e32 v131, v149, v149
	v_mul_f32_e32 v134, v150, v150
	v_fmac_f32_e32 v134, v151, v151
	v_add_f32_e32 v131, v131, v134
	v_add_f32_e32 v130, v130, v131
	v_mul_f32_e32 v131, v152, v152
	v_fmac_f32_e32 v131, v153, v153
	v_mul_f32_e32 v134, v154, v154
	v_fmac_f32_e32 v134, v155, v155
	v_add_f32_e32 v131, v131, v134
	v_add_f32_e32 v130, v130, v131
	v_mul_f32_e32 v131, v156, v156
	v_fmac_f32_e32 v131, v157, v157
	v_mul_f32_e32 v134, v158, v158
	v_fmac_f32_e32 v134, v159, v159
	v_add_f32_e32 v131, v131, v134
	v_add_f32_e32 v130, v130, v131
	v_mul_f32_e32 v131, v160, v160
	v_fmac_f32_e32 v131, v161, v161
	v_mul_f32_e32 v134, v162, v162
	v_fmac_f32_e32 v134, v163, v163
	v_add_f32_e32 v131, v131, v134
	v_add_f32_e32 v130, v130, v131
	v_mul_f32_e32 v131, v164, v164
	v_fmac_f32_e32 v131, v165, v165
	v_mul_f32_e32 v134, v166, v166
	v_fmac_f32_e32 v134, v167, v167
	v_add_f32_e32 v131, v131, v134
	v_add_f32_e32 v130, v130, v131
	v_mul_f32_e32 v131, v168, v168
	v_fmac_f32_e32 v131, v169, v169
	v_mul_f32_e32 v134, v170, v170
	v_fmac_f32_e32 v134, v171, v171
	v_add_f32_e32 v131, v131, v134
	v_add_f32_e32 v130, v130, v131
	v_mul_f32_e32 v131, v172, v172
	v_fmac_f32_e32 v131, v173, v173
	v_mul_f32_e32 v134, v174, v174
	v_fmac_f32_e32 v134, v175, v175
	v_add_f32_e32 v131, v131, v134
	v_add_f32_e32 v130, v130, v131
	ds_bpermute_b32 v131, v208, v130
	s_waitcnt lgkmcnt(0)
	v_add_f32_e32 v130, v130, v131
	ds_bpermute_b32 v131, v209, v130
	s_waitcnt lgkmcnt(0)
	v_add_f32_e32 v130, v130, v131
	ds_bpermute_b32 v131, v210, v130
	s_waitcnt lgkmcnt(0)
	v_add_f32_e32 v130, v130, v131
	ds_bpermute_b32 v131, v211, v130
	s_waitcnt lgkmcnt(0)
	v_add_f32_e32 v130, v130, v131
	ds_bpermute_b32 v131, v212, v130
	s_waitcnt lgkmcnt(0)
	v_add_f32_e32 v130, v130, v131
	ds_bpermute_b32 v131, v213, v130
	s_waitcnt lgkmcnt(0)
	v_add_f32_e32 v130, v130, v131
	v_fmamk_f32 v130, v130, 0x3a000000, v218
	v_mul_f32_e32 v131, 0x4b800000, v130
	v_cmp_gt_f32_e32 vcc, s3, v130
	s_nop 1
	v_cndmask_b32_e32 v130, v130, v131, vcc
	v_rsq_f32_e32 v130, v130
	s_nop 0
	v_mul_f32_e32 v131, 0x45800000, v130
	v_cndmask_b32_e32 v132, v130, v131, vcc
	v_pk_mul_f32 v[144:145], v[144:145], v[132:133] op_sel_hi:[1,0]
	v_pk_mul_f32 v[144:145], v[2:3], v[144:145]
	v_pk_mul_f32 v[146:147], v[146:147], v[132:133] op_sel_hi:[1,0]
	v_pk_mul_f32 v[146:147], v[4:5], v[146:147]
	v_pk_mul_f32 v[148:149], v[148:149], v[132:133] op_sel_hi:[1,0]
	v_pk_mul_f32 v[148:149], v[6:7], v[148:149]
	v_pk_mul_f32 v[150:151], v[150:151], v[132:133] op_sel_hi:[1,0]
	v_pk_mul_f32 v[150:151], v[8:9], v[150:151]
	v_pk_mul_f32 v[152:153], v[152:153], v[132:133] op_sel_hi:[1,0]
	v_pk_mul_f32 v[152:153], v[10:11], v[152:153]
	v_pk_mul_f32 v[154:155], v[154:155], v[132:133] op_sel_hi:[1,0]
	v_pk_mul_f32 v[154:155], v[12:13], v[154:155]
	v_pk_mul_f32 v[156:157], v[156:157], v[132:133] op_sel_hi:[1,0]
	v_pk_mul_f32 v[156:157], v[14:15], v[156:157]
	v_pk_mul_f32 v[158:159], v[158:159], v[132:133] op_sel_hi:[1,0]
	v_pk_mul_f32 v[158:159], v[16:17], v[158:159]
	v_pk_mul_f32 v[160:161], v[160:161], v[132:133] op_sel_hi:[1,0]
	v_pk_mul_f32 v[160:161], v[18:19], v[160:161]
	v_pk_mul_f32 v[162:163], v[162:163], v[132:133] op_sel_hi:[1,0]
	v_pk_mul_f32 v[162:163], v[20:21], v[162:163]
	v_pk_mul_f32 v[164:165], v[164:165], v[132:133] op_sel_hi:[1,0]
	v_pk_mul_f32 v[164:165], v[22:23], v[164:165]
	v_pk_mul_f32 v[166:167], v[166:167], v[132:133] op_sel_hi:[1,0]
	v_pk_mul_f32 v[166:167], v[24:25], v[166:167]
	v_pk_mul_f32 v[168:169], v[168:169], v[132:133] op_sel_hi:[1,0]
	v_pk_mul_f32 v[168:169], v[26:27], v[168:169]
	v_pk_mul_f32 v[170:171], v[170:171], v[132:133] op_sel_hi:[1,0]
	v_pk_mul_f32 v[170:171], v[28:29], v[170:171]
	v_pk_mul_f32 v[172:173], v[172:173], v[132:133] op_sel_hi:[1,0]
	v_pk_mul_f32 v[172:173], v[30:31], v[172:173]
	v_pk_mul_f32 v[174:175], v[174:175], v[132:133] op_sel_hi:[1,0]
	v_pk_mul_f32 v[174:175], v[32:33], v[174:175]
	v_cvt_pk_bf16_f32 v144, v144, v145
	v_cvt_pk_bf16_f32 v145, v146, v147
	v_cvt_pk_bf16_f32 v148, v148, v149
	v_cvt_pk_bf16_f32 v149, v150, v151
	v_cvt_pk_bf16_f32 v152, v152, v153
	v_cvt_pk_bf16_f32 v153, v154, v155
	v_cvt_pk_bf16_f32 v156, v156, v157
	v_cvt_pk_bf16_f32 v157, v158, v159
	v_cvt_pk_bf16_f32 v160, v160, v161
	v_cvt_pk_bf16_f32 v161, v162, v163
	v_cvt_pk_bf16_f32 v164, v164, v165
	v_cvt_pk_bf16_f32 v165, v166, v167
	v_cvt_pk_bf16_f32 v168, v168, v169
	v_cvt_pk_bf16_f32 v169, v170, v171
	v_cvt_pk_bf16_f32 v172, v172, v173
	v_cvt_pk_bf16_f32 v173, v174, v175
	global_store_dwordx2 v[214:215], v[144:145], off offset:0
	global_store_dwordx2 v[214:215], v[148:149], off offset:512
	global_store_dwordx2 v[214:215], v[152:153], off offset:1024
	global_store_dwordx2 v[214:215], v[156:157], off offset:1536
	global_store_dwordx2 v[214:215], v[160:161], off offset:2048
	global_store_dwordx2 v[214:215], v[164:165], off offset:2560
	global_store_dwordx2 v[214:215], v[168:169], off offset:3072
	global_store_dwordx2 v[214:215], v[172:173], off offset:3584
	v_lshl_add_u64 v[214:215], v[214:215], 0, s[0:1]
	s_cmpk_gt_i32 s56, 0x1ff
	s_cbranch_scc1 .LBB0_21
	s_waitcnt vmcnt(32)
	v_mul_f32_e32 v130, v176, v176
	v_fmac_f32_e32 v130, v177, v177
	v_mul_f32_e32 v131, v178, v178
	v_fmac_f32_e32 v131, v179, v179
	v_add_f32_e32 v130, v130, v131
	v_mul_f32_e32 v131, v180, v180
	v_fmac_f32_e32 v131, v181, v181
	v_mul_f32_e32 v134, v182, v182
	v_fmac_f32_e32 v134, v183, v183
	v_add_f32_e32 v131, v131, v134
	v_add_f32_e32 v130, v130, v131
	v_mul_f32_e32 v131, v184, v184
	v_fmac_f32_e32 v131, v185, v185
	v_mul_f32_e32 v134, v186, v186
	v_fmac_f32_e32 v134, v187, v187
	v_add_f32_e32 v131, v131, v134
	v_add_f32_e32 v130, v130, v131
	v_mul_f32_e32 v131, v188, v188
	v_fmac_f32_e32 v131, v189, v189
	v_mul_f32_e32 v134, v190, v190
	v_fmac_f32_e32 v134, v191, v191
	v_add_f32_e32 v131, v131, v134
	v_add_f32_e32 v130, v130, v131
	v_mul_f32_e32 v131, v192, v192
	v_fmac_f32_e32 v131, v193, v193
	v_mul_f32_e32 v134, v194, v194
	v_fmac_f32_e32 v134, v195, v195
	v_add_f32_e32 v131, v131, v134
	v_add_f32_e32 v130, v130, v131
	v_mul_f32_e32 v131, v196, v196
	v_fmac_f32_e32 v131, v197, v197
	v_mul_f32_e32 v134, v198, v198
	v_fmac_f32_e32 v134, v199, v199
	v_add_f32_e32 v131, v131, v134
	v_add_f32_e32 v130, v130, v131
	v_mul_f32_e32 v131, v200, v200
	v_fmac_f32_e32 v131, v201, v201
	v_mul_f32_e32 v134, v202, v202
	v_fmac_f32_e32 v134, v203, v203
	v_add_f32_e32 v131, v131, v134
	v_add_f32_e32 v130, v130, v131
	v_mul_f32_e32 v131, v204, v204
	v_fmac_f32_e32 v131, v205, v205
	v_mul_f32_e32 v134, v206, v206
	v_fmac_f32_e32 v134, v207, v207
	v_add_f32_e32 v131, v131, v134
	v_add_f32_e32 v130, v130, v131
	ds_bpermute_b32 v131, v208, v130
	s_waitcnt lgkmcnt(0)
	v_add_f32_e32 v130, v130, v131
	ds_bpermute_b32 v131, v209, v130
	s_waitcnt lgkmcnt(0)
	v_add_f32_e32 v130, v130, v131
	ds_bpermute_b32 v131, v210, v130
	s_waitcnt lgkmcnt(0)
	v_add_f32_e32 v130, v130, v131
	ds_bpermute_b32 v131, v211, v130
	s_waitcnt lgkmcnt(0)
	v_add_f32_e32 v130, v130, v131
	ds_bpermute_b32 v131, v212, v130
	s_waitcnt lgkmcnt(0)
	v_add_f32_e32 v130, v130, v131
	ds_bpermute_b32 v131, v213, v130
	s_waitcnt lgkmcnt(0)
	v_add_f32_e32 v130, v130, v131
	v_fmamk_f32 v130, v130, 0x3a000000, v218
	v_mul_f32_e32 v131, 0x4b800000, v130
	v_cmp_gt_f32_e32 vcc, s3, v130
	s_nop 1
	v_cndmask_b32_e32 v130, v130, v131, vcc
	v_rsq_f32_e32 v130, v130
	s_nop 0
	v_mul_f32_e32 v131, 0x45800000, v130
	v_cndmask_b32_e32 v132, v130, v131, vcc
	v_pk_mul_f32 v[176:177], v[176:177], v[132:133] op_sel_hi:[1,0]
	v_pk_mul_f32 v[176:177], v[2:3], v[176:177]
	v_pk_mul_f32 v[178:179], v[178:179], v[132:133] op_sel_hi:[1,0]
	v_pk_mul_f32 v[178:179], v[4:5], v[178:179]
	v_pk_mul_f32 v[180:181], v[180:181], v[132:133] op_sel_hi:[1,0]
	v_pk_mul_f32 v[180:181], v[6:7], v[180:181]
	v_pk_mul_f32 v[182:183], v[182:183], v[132:133] op_sel_hi:[1,0]
	v_pk_mul_f32 v[182:183], v[8:9], v[182:183]
	v_pk_mul_f32 v[184:185], v[184:185], v[132:133] op_sel_hi:[1,0]
	v_pk_mul_f32 v[184:185], v[10:11], v[184:185]
	v_pk_mul_f32 v[186:187], v[186:187], v[132:133] op_sel_hi:[1,0]
	v_pk_mul_f32 v[186:187], v[12:13], v[186:187]
	v_pk_mul_f32 v[188:189], v[188:189], v[132:133] op_sel_hi:[1,0]
	v_pk_mul_f32 v[188:189], v[14:15], v[188:189]
	v_pk_mul_f32 v[190:191], v[190:191], v[132:133] op_sel_hi:[1,0]
	v_pk_mul_f32 v[190:191], v[16:17], v[190:191]
	v_pk_mul_f32 v[192:193], v[192:193], v[132:133] op_sel_hi:[1,0]
	v_pk_mul_f32 v[192:193], v[18:19], v[192:193]
	v_pk_mul_f32 v[194:195], v[194:195], v[132:133] op_sel_hi:[1,0]
	v_pk_mul_f32 v[194:195], v[20:21], v[194:195]
	v_pk_mul_f32 v[196:197], v[196:197], v[132:133] op_sel_hi:[1,0]
	v_pk_mul_f32 v[196:197], v[22:23], v[196:197]
	v_pk_mul_f32 v[198:199], v[198:199], v[132:133] op_sel_hi:[1,0]
	v_pk_mul_f32 v[198:199], v[24:25], v[198:199]
	v_pk_mul_f32 v[200:201], v[200:201], v[132:133] op_sel_hi:[1,0]
	v_pk_mul_f32 v[200:201], v[26:27], v[200:201]
	v_pk_mul_f32 v[202:203], v[202:203], v[132:133] op_sel_hi:[1,0]
	v_pk_mul_f32 v[202:203], v[28:29], v[202:203]
	v_pk_mul_f32 v[204:205], v[204:205], v[132:133] op_sel_hi:[1,0]
	v_pk_mul_f32 v[204:205], v[30:31], v[204:205]
	v_pk_mul_f32 v[206:207], v[206:207], v[132:133] op_sel_hi:[1,0]
	v_pk_mul_f32 v[206:207], v[32:33], v[206:207]
	v_cvt_pk_bf16_f32 v176, v176, v177
	v_cvt_pk_bf16_f32 v177, v178, v179
	v_cvt_pk_bf16_f32 v180, v180, v181
	v_cvt_pk_bf16_f32 v181, v182, v183
	v_cvt_pk_bf16_f32 v184, v184, v185
	v_cvt_pk_bf16_f32 v185, v186, v187
	v_cvt_pk_bf16_f32 v188, v188, v189
	v_cvt_pk_bf16_f32 v189, v190, v191
	v_cvt_pk_bf16_f32 v192, v192, v193
	v_cvt_pk_bf16_f32 v193, v194, v195
	v_cvt_pk_bf16_f32 v196, v196, v197
	v_cvt_pk_bf16_f32 v197, v198, v199
	v_cvt_pk_bf16_f32 v200, v200, v201
	v_cvt_pk_bf16_f32 v201, v202, v203
	v_cvt_pk_bf16_f32 v204, v204, v205
	v_cvt_pk_bf16_f32 v205, v206, v207
	global_store_dwordx2 v[214:215], v[176:177], off offset:0
	global_store_dwordx2 v[214:215], v[180:181], off offset:512
	global_store_dwordx2 v[214:215], v[184:185], off offset:1024
	global_store_dwordx2 v[214:215], v[188:189], off offset:1536
	global_store_dwordx2 v[214:215], v[192:193], off offset:2048
	global_store_dwordx2 v[214:215], v[196:197], off offset:2560
	global_store_dwordx2 v[214:215], v[200:201], off offset:3072
	global_store_dwordx2 v[214:215], v[204:205], off offset:3584
	v_lshl_add_u64 v[214:215], v[214:215], 0, s[0:1]
